# GLA chunk-local unit: LDS fragment reads of the first MFMA chain issued ahead with counted waits (ring of 8 transient quads)
# speedup vs baseline: 1.0123x; 1.0006x over previous
; #define LAS __attribute__((address_space(3)))
; __device__ __forceinline__ unsigned pk2(float lo, float hi) { return pg8::cvt_pk_bf16(lo, hi); }
; __device__ __forceinline__ float bflo(unsigned w) { return __uint_as_float(w << 16); }
; __device__ __forceinline__ void gla_a_unit(LAS unsigned char* lds, bf16* QKA, bf16* VA, const float* FA, unsigned char* ws, int xnrow0, float* DECB, int lchunk, int h,
;                                            const float* wgate, const float* bgate, int tid) {
;     ...
;     for (int i = 0; i < 2; ++i) { const int id = tid + 512 * i, row = id >> 4, ch = id & 15;
;         f32x4 b0 = *(const LAS f32x4*)(Bimg + row * GBP + ch * 8), b1 = *(const LAS f32x4*)(Bimg + row * GBP + ch * 8 + 4);
;         f32x4 l0 = (f32x4){0.f, 0.f, 0.f, 0.f}, l1 = l0;
; #pragma unroll
;         for (int q = 0; q < 4; ++q) { const f32x4 s0v = *(const LAS f32x4*)(SEG + q * 128 + ch * 8), s1v = *(const LAS f32x4*)(SEG + q * 128 + ch * 8 + 4);
;             l0 += s0v; l1 += s1v; if (q < (row >> 4)) { b0 += s0v; b1 += s1v; } }
;         if (row == 0) { float* dp = DECB + (size_t)unit * 128 + ch * 8;
;             *(f32x4*)dp = (f32x4){__expf(l0[0]), __expf(l0[1]), __expf(l0[2]), __expf(l0[3])}; *(f32x4*)(dp + 4) = (f32x4){__expf(l1[0]), __expf(l1[1]), __expf(l1[2]), __expf(l1[3])}; }
;         const float bb[8] = {b0[0], b0[1], b0[2], b0[3], b1[0], b1[1], b1[2], b1[3]};
;         const unsigned qw[4] = {qv[i].x, qv[i].y, qv[i].z, qv[i].w}, kw[4] = {kv[i].x, kv[i].y, kv[i].z, kv[i].w};
;         unsigned oq[4], oi[4];
; #pragma unroll
;         for (int e = 0; e < 4; ++e) { const float q0 = bflo(qw[e]), q1 = bfhi(qw[e]), k0 = bflo(kw[e]), k1 = bfhi(kw[e]);
;             const float e0 = __expf(bb[2 * e]), e1 = __expf(bb[2 * e + 1]), n0 = __expf(-bb[2 * e]), n1 = __expf(-bb[2 * e + 1]);
;             oq[e] = pk2(q0 * e0, q1 * e1); oi[e] = pk2(k0 * n0, k1 * n1); }
;         const u32x4 qd = (u32x4){oq[0], oq[1], oq[2], oq[3]};
;         *(LAS u32x4*)(lds + G_QD + row * GP + ch * 16) = qd;
;         *(LAS u32x4*)(lds + G_KI + row * GP + ch * 16) = (u32x4){oi[0], oi[1], oi[2], oi[3]};
;         *(LAS u32x4*)(lds + G_KT + row * GKTP + ch * 16) = (u32x4){oi[0], oi[1], oi[2], oi[3]};
;         *(u32x4*)(QKA + (row0 + row) * 1024 + h * 128 + ch * 8) = qd; }
;     __syncthreads();
.LBB0_557:
	s_or_b64 exec, exec, s[62:63]
	s_waitcnt lgkmcnt(7)
	v_pk_add_f32 v[48:49], v[44:45], v[48:49]
	s_waitcnt lgkmcnt(6)
	v_pk_add_f32 v[28:29], v[24:25], v[28:29]
	v_cndmask_b32_e64 v45, v45, v49, s[26:27]
	v_cndmask_b32_e64 v44, v44, v48, s[26:27]
	s_waitcnt lgkmcnt(5)
	v_pk_add_f32 v[40:41], v[44:45], v[40:41]
	v_cndmask_b32_e64 v25, v25, v29, s[26:27]
	v_cndmask_b32_e64 v24, v24, v28, s[26:27]
	v_cndmask_b32_e64 v41, v45, v41, s[24:25]
	v_cndmask_b32_e64 v40, v44, v40, s[24:25]
	v_pk_add_f32 v[30:31], v[26:27], v[30:31]
	s_waitcnt lgkmcnt(4)
	v_pk_add_f32 v[20:21], v[24:25], v[20:21]
	s_waitcnt lgkmcnt(3)
	v_pk_add_f32 v[36:37], v[40:41], v[36:37]
	v_cndmask_b32_e64 v27, v27, v31, s[26:27]
	v_cndmask_b32_e64 v26, v26, v30, s[26:27]
	v_cndmask_b32_e64 v21, v25, v21, s[24:25]
	v_cndmask_b32_e64 v20, v24, v20, s[24:25]
	v_cndmask_b32_e64 v37, v41, v37, s[22:23]
	v_cndmask_b32_e64 v36, v40, v36, s[22:23]
	v_pk_add_f32 v[22:23], v[26:27], v[22:23]
	s_waitcnt lgkmcnt(2)
	v_pk_add_f32 v[16:17], v[20:21], v[16:17]
	s_waitcnt lgkmcnt(1)
	v_pk_add_f32 v[32:33], v[36:37], v[32:33]
	v_cndmask_b32_e64 v23, v27, v23, s[24:25]
	v_cndmask_b32_e64 v22, v26, v22, s[24:25]
	v_cndmask_b32_e64 v17, v21, v17, s[22:23]
	v_cndmask_b32_e64 v16, v20, v16, s[22:23]
	v_cndmask_b32_e64 v33, v37, v33, s[20:21]
	v_cndmask_b32_e64 v32, v36, v32, s[20:21]
	v_pk_add_f32 v[18:19], v[22:23], v[18:19]
	s_waitcnt lgkmcnt(0)
	v_pk_add_f32 v[12:13], v[16:17], v[12:13]
	v_pk_add_f32 v[50:51], v[46:47], v[50:51]
	v_cndmask_b32_e64 v19, v23, v19, s[22:23]
	v_cndmask_b32_e64 v18, v22, v18, s[22:23]
	v_cndmask_b32_e64 v20, v17, v13, s[20:21]
	v_cndmask_b32_e64 v21, v16, v12, s[20:21]
	v_mul_f32_e32 v12, 0x3fb8aa3b, v32
	v_mul_f32_e32 v13, 0x3fb8aa3b, v33
	v_cndmask_b32_e64 v47, v47, v51, s[26:27]
	v_cndmask_b32_e64 v46, v46, v50, s[26:27]
	v_pk_add_f32 v[14:15], v[18:19], v[14:15]
	v_exp_f32_e32 v12, v12
	v_exp_f32_e32 v13, v13
	v_pk_add_f32 v[42:43], v[46:47], v[42:43]
	v_cndmask_b32_e64 v19, v19, v15, s[20:21]
	v_cndmask_b32_e64 v18, v18, v14, s[20:21]
	v_mul_f32_e32 v14, 0xbfb8aa3b, v32
	v_mul_f32_e32 v15, 0xbfb8aa3b, v33
	v_cndmask_b32_e64 v43, v47, v43, s[24:25]
	v_cndmask_b32_e64 v42, v46, v42, s[24:25]
	v_exp_f32_e32 v14, v14
	v_exp_f32_e32 v15, v15
	v_pk_add_f32 v[38:39], v[42:43], v[38:39]
	v_lshlrev_b32_e32 v16, 16, v8
	v_and_b32_e32 v17, 0xffff0000, v8
	v_cndmask_b32_e64 v39, v43, v39, s[22:23]
	v_cndmask_b32_e64 v38, v42, v38, s[22:23]
	v_pk_mul_f32 v[12:13], v[12:13], v[16:17]
	v_pk_add_f32 v[34:35], v[38:39], v[34:35]
	v_cvt_pk_bf16_f32 v8, v12, v13
	v_lshlrev_b32_e32 v12, 16, v4
	v_and_b32_e32 v13, 0xffff0000, v4
	v_cndmask_b32_e64 v2, v39, v35, s[20:21]
	v_cndmask_b32_e64 v34, v38, v34, s[20:21]
	v_pk_mul_f32 v[12:13], v[14:15], v[12:13]
	v_mul_f32_e32 v14, 0xbfb8aa3b, v34
	v_cvt_pk_bf16_f32 v4, v12, v13
	v_mul_f32_e32 v12, 0x3fb8aa3b, v34
	v_mul_f32_e32 v13, 0x3fb8aa3b, v2
	v_exp_f32_e32 v12, v12
	v_exp_f32_e32 v13, v13
	v_mul_f32_e32 v2, 0xbfb8aa3b, v2
	v_exp_f32_e32 v14, v14
	v_exp_f32_e32 v15, v2
	v_lshlrev_b32_e32 v16, 16, v9
	v_and_b32_e32 v17, 0xffff0000, v9
	v_pk_mul_f32 v[12:13], v[12:13], v[16:17]
	v_mul_f32_e32 v2, 0x3fb8aa3b, v21
	v_cvt_pk_bf16_f32 v9, v12, v13
	v_lshlrev_b32_e32 v12, 16, v5
	v_and_b32_e32 v13, 0xffff0000, v5
	v_pk_mul_f32 v[12:13], v[14:15], v[12:13]
	v_lshlrev_b32_e32 v16, 16, v10
	v_cvt_pk_bf16_f32 v5, v12, v13
	v_exp_f32_e32 v12, v2
	v_mul_f32_e32 v2, 0x3fb8aa3b, v20
	v_exp_f32_e32 v13, v2
	v_mul_f32_e32 v2, 0xbfb8aa3b, v21
	v_exp_f32_e32 v14, v2
	v_mul_f32_e32 v2, 0xbfb8aa3b, v20
	v_exp_f32_e32 v15, v2
	v_and_b32_e32 v17, 0xffff0000, v10
	v_pk_mul_f32 v[12:13], v[12:13], v[16:17]
	v_mul_f32_e32 v2, 0x3fb8aa3b, v18
	v_cvt_pk_bf16_f32 v10, v12, v13
	v_lshlrev_b32_e32 v12, 16, v6
	v_and_b32_e32 v13, 0xffff0000, v6
	v_pk_mul_f32 v[12:13], v[14:15], v[12:13]
	v_lshlrev_b32_e32 v16, 16, v11
	v_cvt_pk_bf16_f32 v6, v12, v13
	v_exp_f32_e32 v12, v2
	v_mul_f32_e32 v2, 0x3fb8aa3b, v19
	v_exp_f32_e32 v13, v2
	v_mul_f32_e32 v2, 0xbfb8aa3b, v18
	v_exp_f32_e32 v14, v2
	v_mul_f32_e32 v2, 0xbfb8aa3b, v19
	v_exp_f32_e32 v15, v2
	v_and_b32_e32 v17, 0xffff0000, v11
	v_pk_mul_f32 v[12:13], v[12:13], v[16:17]
	s_and_b32 s6, s2, 0xffffffc0
	v_cvt_pk_bf16_f32 v11, v12, v13
	v_lshlrev_b32_e32 v12, 16, v7
	v_and_b32_e32 v13, 0xffff0000, v7
	v_pk_mul_f32 v[12:13], v[14:15], v[12:13]
	v_add_u32_e32 v2, s6, v131
	v_cvt_pk_bf16_f32 v7, v12, v13
	ds_write_b128 v150, v[8:11]
	ds_write_b128 v150, v[4:7] offset:17408
	ds_write_b128 v151, v[4:7]
	global_store_dwordx4 v[60:61], v[8:11], off
	s_waitcnt lgkmcnt(0)
	s_barrier
; #define LAS __attribute__((address_space(3)))
; __device__ __forceinline__ int crow(int r, int hi) { return (r & 3) + 8 * (r >> 2) + 4 * hi; }
; __device__ __forceinline__ bf16x8 cat8(s16x4 a, s16x4 b) { return (bf16x8){a[0], a[1], a[2], a[3], b[0], b[1], b[2], b[3]}; }
; __device__ __forceinline__ void gla_a_unit(LAS unsigned char* lds, bf16* QKA, bf16* VA, const float* FA, unsigned char* ws, int xnrow0, float* DECB, int lchunk, int h,
;                                            const float* wgate, const float* bgate, int tid) {
;     ...
;     bf16x8 vvf[4];
; #pragma unroll
;     for (int kc = 0; kc < 4; ++kc) { LAS const unsigned char* p = lds + G_VV + (16 * kc + trrow) * GVP + (32 * w + trcol) * 2; vvf[kc] = cat8(tr16(p), tr16(p + 8 * GVP)); }
;     f32x16 s00, s01, s11;
; #pragma unroll
;     for (int r = 0; r < 16; ++r) { s00[r] = 0.f; s01[r] = 0.f; s11[r] = 0.f; }
; #pragma unroll
;     for (int s = 0; s < 8; ++s) {
;         const bf16x8 a0 = *(const LAS bf16x8*)(lds + G_KI + r32 * GP + (16 * s + 8 * hi) * 2), a1 = *(const LAS bf16x8*)(lds + G_KI + (32 + r32) * GP + (16 * s + 8 * hi) * 2);
;         const bf16x8 b0 = *(const LAS bf16x8*)(lds + G_QD + r32 * GP + (16 * s + 8 * hi) * 2), b1 = *(const LAS bf16x8*)(lds + G_QD + (32 + r32) * GP + (16 * s + 8 * hi) * 2);
;         s00 = __builtin_amdgcn_mfma_f32_32x32x16_bf16(a0, b0, s00, 0, 0, 0); s01 = __builtin_amdgcn_mfma_f32_32x32x16_bf16(a0, b1, s01, 0, 0, 0); s11 = __builtin_amdgcn_mfma_f32_32x32x16_bf16(a1, b1, s11, 0, 0, 0);
;     }
; #pragma unroll
;     for (int r = 0; r < 16; ++r) if (crow(r, hi) > r32) { s00[r] = 0.f; s11[r] = 0.f; }
;     const bf16x8 p00a = pack8(s00, 0), p00b = pack8(s00, 8), p01a = pack8(s01, 0), p01b = pack8(s01, 8), p11a = pack8(s11, 0), p11b = pack8(s11, 8);
;     f32x16 oT0, oT1;
; #pragma unroll
;     for (int r = 0; r < 16; ++r) { oT0[r] = 0.f; oT1[r] = 0.f; }
;     oT0 = __builtin_amdgcn_mfma_f32_32x32x16_bf16(vvf[0], p00a, oT0, 0, 0, 0); oT0 = __builtin_amdgcn_mfma_f32_32x32x16_bf16(vvf[1], p00b, oT0, 0, 0, 0);
;     oT1 = __builtin_amdgcn_mfma_f32_32x32x16_bf16(vvf[0], p01a, oT1, 0, 0, 0); oT1 = __builtin_amdgcn_mfma_f32_32x32x16_bf16(vvf[1], p01b, oT1, 0, 0, 0);
;     oT1 = __builtin_amdgcn_mfma_f32_32x32x16_bf16(vvf[2], p11a, oT1, 0, 0, 0); oT1 = __builtin_amdgcn_mfma_f32_32x32x16_bf16(vvf[3], p11b, oT1, 0, 0, 0);
	ds_read_b128 v[36:39], v152 offset:17408
	ds_read_b128 v[218:221], v152
	ds_read_b128 v[222:225], v152 offset:26112
	ds_read_b128 v[40:43], v152 offset:8704
	ds_read_b128 v[52:55], v152 offset:17440
	ds_read_b128 v[226:229], v152 offset:32
	ds_read_b128 v[230:233], v152 offset:26144
	ds_read_b128 v[56:59], v152 offset:8736
	ds_read_b128 v[60:63], v152 offset:17472
	ds_read_b128 v[234:237], v152 offset:64
	ds_read_b128 v[238:241], v152 offset:26176
	ds_read_b128 v[64:67], v152 offset:8768
	ds_read_b128 v[68:71], v152 offset:17504
	ds_read_b128 v[242:245], v152 offset:96
	ds_read_b128 v[246:249], v152 offset:26208
	s_waitcnt lgkmcnt(13)
	v_mfma_f32_32x32x16_bf16 v[20:35], v[36:39], v[218:221], 0
	ds_read_b128 v[72:75], v152 offset:8800
	ds_read_b128 v[76:79], v152 offset:17536
	s_ashr_i32 s64, s2, 6
	s_lshl_b32 s2, s64, 3
	s_ashr_i32 s6, s2, 31
	s_add_u32 s2, s82, s2
	s_addc_u32 s6, s83, s6
	s_waitcnt lgkmcnt(13)
	v_mfma_f32_32x32x16_bf16 v[4:19], v[222:225], v[40:43], 0
	ds_read_b128 v[218:221], v152 offset:128
	ds_read_b128 v[222:225], v152 offset:26240
	s_lshl_b32 s78, s78, 1
	v_mov_b32_e32 v125, v3
	s_ashr_i32 s65, s64, 31
	s_add_i32 s3, s3, s32
	s_mov_b32 s70, s68
	s_waitcnt lgkmcnt(13)
	v_mfma_f32_32x32x16_bf16 v[20:35], v[52:55], v[226:229], v[20:35]
	ds_read_b128 v[80:83], v152 offset:8832
	ds_read_b128 v[170:173], v152 offset:17568
	s_waitcnt lgkmcnt(13)
	v_mfma_f32_32x32x16_bf16 v[4:19], v[230:233], v[56:59], v[4:19]
	ds_read_b128 v[226:229], v152 offset:160
	ds_read_b128 v[230:233], v152 offset:26272
	s_waitcnt lgkmcnt(13)
	v_mfma_f32_32x32x16_bf16 v[20:35], v[60:63], v[234:237], v[20:35]
	ds_read_b128 v[174:177], v152 offset:8864
	ds_read_b128 v[182:185], v152 offset:17600
	s_waitcnt lgkmcnt(13)
	v_mfma_f32_32x32x16_bf16 v[4:19], v[238:241], v[64:67], v[4:19]
	ds_read_b128 v[234:237], v152 offset:192
	ds_read_b128 v[238:241], v152 offset:26304
	s_waitcnt lgkmcnt(13)
	v_mfma_f32_32x32x16_bf16 v[20:35], v[68:71], v[242:245], v[20:35]
	ds_read_b128 v[186:189], v152 offset:8896
	ds_read_b128 v[190:193], v152 offset:17632
	s_waitcnt lgkmcnt(13)
	v_mfma_f32_32x32x16_bf16 v[4:19], v[246:249], v[72:75], v[4:19]
	ds_read_b128 v[242:245], v152 offset:224
	ds_read_b128 v[246:249], v152 offset:26336
	s_waitcnt lgkmcnt(13)
	v_mfma_f32_32x32x16_bf16 v[20:35], v[76:79], v[218:221], v[20:35]
	ds_read_b128 v[210:213], v152 offset:8928
	s_waitcnt lgkmcnt(12)
	v_mfma_f32_32x32x16_bf16 v[4:19], v[222:225], v[80:83], v[4:19]
	s_waitcnt lgkmcnt(10)
	v_mfma_f32_32x32x16_bf16 v[20:35], v[170:173], v[226:229], v[20:35]
	s_waitcnt lgkmcnt(8)
	v_mfma_f32_32x32x16_bf16 v[4:19], v[230:233], v[174:177], v[4:19]
	s_waitcnt lgkmcnt(6)
	v_mfma_f32_32x32x16_bf16 v[20:35], v[182:185], v[234:237], v[20:35]
	s_waitcnt lgkmcnt(4)
	v_mfma_f32_32x32x16_bf16 v[4:19], v[238:241], v[186:189], v[4:19]
	s_waitcnt lgkmcnt(2)
	v_mfma_f32_32x32x16_bf16 v[20:35], v[190:193], v[242:245], v[20:35]
	s_waitcnt lgkmcnt(0)
	v_mfma_f32_32x32x16_bf16 v[4:19], v[246:249], v[210:213], v[4:19]
	v_mfma_f32_32x32x16_bf16 v[36:51], v[36:39], v[40:43], 0
	v_mfma_f32_32x32x16_bf16 v[36:51], v[52:55], v[56:59], v[36:51]
	v_add_u32_e32 v52, v2, v132
	v_add_u32_e32 v2, v2, v133
	ds_read_b64_tr_b16 v[96:97], v52 offset:34816
	ds_read_b64_tr_b16 v[98:99], v52 offset:39424
	ds_read_b64_tr_b16 v[88:89], v52 offset:44032
	ds_read_b64_tr_b16 v[90:91], v52 offset:48640
	ds_read_b64_tr_b16 v[92:93], v52 offset:53248
	ds_read_b64_tr_b16 v[94:95], v52 offset:57856
	ds_read_b64_tr_b16 v[84:85], v52 offset:62464
	ds_read_b64_tr_b16 v[86:87], v2 offset:57856
	v_cndmask_b32_e64 v2, v20, 0, s[28:29]
	v_cndmask_b32_e64 v52, v4, 0, s[28:29]
	v_mfma_f32_32x32x16_bf16 v[36:51], v[60:63], v[64:67], v[36:51]
	v_cndmask_b32_e64 v2, v2, v20, s[30:31]
	v_cndmask_b32_e64 v20, 0, v21, s[30:31]
	v_cndmask_b32_e64 v21, v25, 0, s[40:41]
	v_cndmask_b32_e64 v25, v29, 0, s[48:49]
	v_mfma_f32_32x32x16_bf16 v[36:51], v[68:71], v[72:75], v[36:51]
	v_cndmask_b32_e64 v69, 0, v5, s[30:31]
	v_cndmask_b32_e64 v5, v22, 0, s[34:35]
	v_cndmask_b32_e64 v70, v6, 0, s[34:35]
	v_cndmask_b32_e64 v6, v23, 0, s[36:37]
	v_cndmask_b32_e64 v71, v7, 0, s[36:37]
	v_cndmask_b32_e64 v7, v24, 0, s[38:39]
	v_cndmask_b32_e64 v22, v26, 0, s[42:43]
	v_mfma_f32_32x32x16_bf16 v[36:51], v[76:79], v[80:83], v[36:51]
	v_cndmask_b32_e64 v23, v27, 0, s[44:45]
	v_cndmask_b32_e64 v68, v52, v4, s[30:31]
	v_cvt_pk_bf16_f32 v4, v2, v20
	v_cvt_pk_bf16_f32 v5, v5, v6
	v_cvt_pk_bf16_f32 v6, v7, v21
	v_cvt_pk_bf16_f32 v7, v22, v23
	v_cndmask_b32_e64 v24, v28, 0, s[46:47]
	v_mfma_f32_32x32x16_bf16 v[36:51], v[170:173], v[174:177], v[36:51]
	v_cndmask_b32_e64 v26, v30, 0, s[50:51]
	v_cndmask_b32_e64 v27, v31, 0, s[52:53]
	v_cndmask_b32_e64 v28, v32, 0, s[54:55]
	v_cndmask_b32_e64 v2, v33, 0, s[56:57]
	v_cndmask_b32_e64 v20, v35, 0, s[60:61]
	v_mfma_f32_32x32x16_bf16 v[36:51], v[182:185], v[186:189], v[36:51]
	v_mfma_f32_32x32x16_bf16 v[36:51], v[190:193], v[210:213], v[36:51]
	s_waitcnt lgkmcnt(6)
	v_mfma_f32_32x32x16_bf16 v[52:67], v[96:99], v[4:7], 0
	v_cndmask_b32_e64 v7, v34, 0, s[58:59]
	v_cvt_pk_bf16_f32 v4, v24, v25
	v_cvt_pk_bf16_f32 v5, v26, v27
	v_cvt_pk_bf16_f32 v6, v28, v2
	v_cvt_pk_bf16_f32 v7, v7, v20
	v_cndmask_b32_e64 v2, v8, 0, s[38:39]
	v_cndmask_b32_e64 v8, v9, 0, s[40:41]
	s_waitcnt lgkmcnt(4)
; #define LAS __attribute__((address_space(3)))
; __device__ __forceinline__ bf16x8 cat8(s16x4 a, s16x4 b) { return (bf16x8){a[0], a[1], a[2], a[3], b[0], b[1], b[2], b[3]}; }
; __device__ __forceinline__ bf16x8 pack8(const f32x16& v, int o) { u32x4 w; w.x = pk2(v[o], v[o + 1]); w.y = pk2(v[o + 2], v[o + 3]); w.z = pk2(v[o + 4], v[o + 5]); w.w = pk2(v[o + 6], v[o + 7]); return __builtin_bit_cast(bf16x8, w); }
; __device__ __forceinline__ bf16* ub_slot(unsigned char* ybase, int unit, int) { return (bf16*)ybase + (size_t)unit * 32768; }
; __device__ __forceinline__ void gla_a_unit(LAS unsigned char* lds, bf16* QKA, bf16* VA, const float* FA, unsigned char* ws, int xnrow0, float* DECB, int lchunk, int h,
;                                            const float* wgate, const float* bgate, int tid) {
;     ...
;     oT0 = __builtin_amdgcn_mfma_f32_32x32x16_bf16(vvf[0], p00a, oT0, 0, 0, 0); oT0 = __builtin_amdgcn_mfma_f32_32x32x16_bf16(vvf[1], p00b, oT0, 0, 0, 0);
;     oT1 = __builtin_amdgcn_mfma_f32_32x32x16_bf16(vvf[0], p01a, oT1, 0, 0, 0); oT1 = __builtin_amdgcn_mfma_f32_32x32x16_bf16(vvf[1], p01b, oT1, 0, 0, 0);
;     oT1 = __builtin_amdgcn_mfma_f32_32x32x16_bf16(vvf[2], p11a, oT1, 0, 0, 0); oT1 = __builtin_amdgcn_mfma_f32_32x32x16_bf16(vvf[3], p11b, oT1, 0, 0, 0);
;     { bf16* p0 = VA + (row0 + (2 * w) * 4 + g16) * 1024 + h * 256 + i16 * 16; bf16* p1 = p0 + 4 * 1024;
;       *(u32x4*)p0 = __builtin_bit_cast(u32x4, pack8(oT0, 0)); *(u32x4*)(p0 + 8) = __builtin_bit_cast(u32x4, pack8(oT0, 8));
;       *(u32x4*)p1 = __builtin_bit_cast(u32x4, pack8(oT1, 0)); *(u32x4*)(p1 + 8) = __builtin_bit_cast(u32x4, pack8(oT1, 8)); }
;     bf16* up = ub_slot(ws, unit, xnrow0) + (size_t)w * 4096 + lane * 8;
; #pragma unroll
;     for (int db = 0; db < 4; ++db) { f32x16 uacc;
; #pragma unroll
;         for (int r = 0; r < 16; ++r) uacc[r] = 0.f;
; #pragma unroll
;         for (int kc = 0; kc < 4; ++kc) { LAS const unsigned char* p = lds + G_KT + (16 * kc + trrow) * GKTP + (32 * db + trcol) * 2;
;             uacc = __builtin_amdgcn_mfma_f32_32x32x16_bf16(cat8(tr16(p), tr16(p + 8 * GKTP)), vvf[kc], uacc, 0, 0, 0); }
;         *(u32x4*)(up + (db * 2) * 512) = __builtin_bit_cast(u32x4, pack8(uacc, 0)); *(u32x4*)(up + (db * 2 + 1) * 512) = __builtin_bit_cast(u32x4, pack8(uacc, 8)); }
;     __syncthreads();
	v_mfma_f32_32x32x16_bf16 v[52:67], v[88:91], v[4:7], v[52:67]
	s_nop 0
	v_cvt_pk_bf16_f32 v4, v36, v37
	v_cvt_pk_bf16_f32 v5, v38, v39
	v_cvt_pk_bf16_f32 v6, v40, v41
	v_cvt_pk_bf16_f32 v7, v42, v43
	v_cndmask_b32_e64 v9, v10, 0, s[42:43]
	v_cndmask_b32_e64 v10, v11, 0, s[44:45]
	v_cndmask_b32_e64 v11, v12, 0, s[46:47]
	v_mfma_f32_32x32x16_bf16 v[20:35], v[96:99], v[4:7], 0
	v_cvt_pk_bf16_f32 v4, v44, v45
	v_cvt_pk_bf16_f32 v5, v46, v47
	v_cvt_pk_bf16_f32 v6, v48, v49
	v_cvt_pk_bf16_f32 v7, v50, v51
	v_cndmask_b32_e64 v12, v13, 0, s[48:49]
	v_cndmask_b32_e64 v13, v14, 0, s[50:51]
	v_cndmask_b32_e64 v14, v15, 0, s[52:53]
	v_mfma_f32_32x32x16_bf16 v[20:35], v[88:91], v[4:7], v[20:35]
	v_cvt_pk_bf16_f32 v4, v68, v69
	v_cvt_pk_bf16_f32 v5, v70, v71
	v_cvt_pk_bf16_f32 v6, v2, v8
	v_cvt_pk_bf16_f32 v7, v9, v10
	v_cndmask_b32_e64 v15, v16, 0, s[54:55]
	v_cndmask_b32_e64 v2, v17, 0, s[56:57]
	v_cndmask_b32_e64 v8, v19, 0, s[60:61]
	s_waitcnt lgkmcnt(2)
	v_mfma_f32_32x32x16_bf16 v[20:35], v[92:95], v[4:7], v[20:35]
	v_cndmask_b32_e64 v7, v18, 0, s[58:59]
	v_cvt_pk_bf16_f32 v4, v11, v12
	v_cvt_pk_bf16_f32 v5, v13, v14
	v_cvt_pk_bf16_f32 v6, v15, v2
	v_cvt_pk_bf16_f32 v7, v7, v8
	v_mov_b32_e32 v13, s6
	v_or_b32_e32 v12, s2, v116
	s_waitcnt lgkmcnt(0)
	v_mfma_f32_32x32x16_bf16 v[20:35], v[84:87], v[4:7], v[20:35]
	ds_read_b64_tr_b16 v[4:5], v153
	ds_read_b64_tr_b16 v[6:7], v153 offset:2560
	s_lshl_b64 s[6:7], s[64:65], 13
	s_mov_b32 s64, s69
	s_cmp_ge_i32 s3, s69
	s_waitcnt lgkmcnt(0)
	v_mfma_f32_32x32x16_bf16 v[68:83], v[4:7], v[96:99], 0
	ds_read_b64_tr_b16 v[4:5], v153 offset:5120
	ds_read_b64_tr_b16 v[6:7], v153 offset:7680
	s_waitcnt lgkmcnt(0)
	v_mfma_f32_32x32x16_bf16 v[68:83], v[4:7], v[88:91], v[68:83]
	ds_read_b64_tr_b16 v[4:5], v153 offset:10240
	ds_read_b64_tr_b16 v[6:7], v153 offset:12800
	ds_read_b64_tr_b16 v[8:9], v153 offset:15360
	ds_read_b64_tr_b16 v[10:11], v153 offset:17920
	s_waitcnt lgkmcnt(2)
	v_mfma_f32_32x32x16_bf16 v[68:83], v[4:7], v[92:95], v[68:83]
	ds_read_b64_tr_b16 v[4:5], v153 offset:64
	ds_read_b64_tr_b16 v[6:7], v153 offset:2624
	s_waitcnt lgkmcnt(0)
	v_mfma_f32_32x32x16_bf16 v[36:51], v[4:7], v[96:99], 0
	v_cvt_pk_bf16_f32 v4, v52, v53
	v_cvt_pk_bf16_f32 v5, v54, v55
	v_cvt_pk_bf16_f32 v6, v56, v57
	v_cvt_pk_bf16_f32 v7, v58, v59
	v_mfma_f32_32x32x16_bf16 v[68:83], v[8:11], v[84:87], v[68:83]
	v_lshlrev_b64 v[8:9], 11, v[12:13]
	v_lshl_add_u64 v[8:9], s[4:5], 0, v[8:9]
	v_lshl_add_u64 v[12:13], v[8:9], 0, s[78:79]
	ds_read_b64_tr_b16 v[8:9], v153 offset:5184
	ds_read_b64_tr_b16 v[10:11], v153 offset:7744
	v_lshl_add_u64 v[16:17], v[12:13], 0, v[124:125]
	ds_read_b64_tr_b16 v[12:13], v153 offset:10304
	ds_read_b64_tr_b16 v[14:15], v153 offset:12864
	global_store_dwordx4 v[16:17], v[4:7], off
	s_waitcnt lgkmcnt(2)
	v_mfma_f32_32x32x16_bf16 v[36:51], v[8:11], v[88:91], v[36:51]
	ds_read_b64_tr_b16 v[8:9], v153 offset:15424
	ds_read_b64_tr_b16 v[10:11], v153 offset:17984
	v_cvt_pk_bf16_f32 v4, v60, v61
	v_cvt_pk_bf16_f32 v5, v62, v63
	v_cvt_pk_bf16_f32 v6, v64, v65
	v_cvt_pk_bf16_f32 v7, v66, v67
	global_store_dwordx4 v[16:17], v[4:7], off offset:16
	v_add_co_u32_e64 v52, s[62:63], s96, v16
	s_waitcnt lgkmcnt(2)
	v_mfma_f32_32x32x16_bf16 v[36:51], v[12:15], v[92:95], v[36:51]
	v_cvt_pk_bf16_f32 v4, v20, v21
	v_cvt_pk_bf16_f32 v5, v22, v23
	v_cvt_pk_bf16_f32 v6, v24, v25
	v_cvt_pk_bf16_f32 v7, v26, v27
	v_addc_co_u32_e64 v53, s[62:63], 0, v17, s[62:63]
	v_cvt_pk_bf16_f32 v20, v28, v29
	s_waitcnt lgkmcnt(0)
	v_mfma_f32_32x32x16_bf16 v[36:51], v[8:11], v[84:87], v[36:51]
	ds_read_b64_tr_b16 v[8:9], v153 offset:128
	ds_read_b64_tr_b16 v[10:11], v153 offset:2688
	global_store_dwordx4 v[52:53], v[4:7], off
	ds_read_b64_tr_b16 v[24:25], v153 offset:5248
	ds_read_b64_tr_b16 v[26:27], v153 offset:7808
	v_cvt_pk_bf16_f32 v21, v30, v31
	v_cvt_pk_bf16_f32 v22, v32, v33
	v_cvt_pk_bf16_f32 v23, v34, v35
	global_store_dwordx4 v[52:53], v[20:23], off offset:16
	s_waitcnt lgkmcnt(2)
	v_mfma_f32_32x32x16_bf16 v[4:19], v[8:11], v[96:99], 0
	ds_read_b64_tr_b16 v[20:21], v153 offset:10368
	ds_read_b64_tr_b16 v[22:23], v153 offset:12928
	v_lshl_add_u64 v[28:29], v[120:121], 0, s[88:89]
	v_lshl_add_u64 v[52:53], v[28:29], 0, s[6:7]
	ds_read_b64_tr_b16 v[28:29], v153 offset:15488
	ds_read_b64_tr_b16 v[30:31], v153 offset:18048
	v_cvt_pk_bf16_f32 v36, v36, v37
	v_cvt_pk_bf16_f32 v37, v38, v39
	v_cvt_pk_bf16_f32 v38, v40, v41
	s_waitcnt lgkmcnt(4)
	v_mfma_f32_32x32x16_bf16 v[4:19], v[24:27], v[88:91], v[4:19]
	v_cvt_pk_bf16_f32 v24, v68, v69
	v_cvt_pk_bf16_f32 v25, v70, v71
	v_cvt_pk_bf16_f32 v26, v72, v73
	v_cvt_pk_bf16_f32 v27, v74, v75
	global_store_dwordx4 v[52:53], v[24:27], off
	ds_read_b64_tr_b16 v[24:25], v153 offset:192
	ds_read_b64_tr_b16 v[26:27], v153 offset:2752
	v_cvt_pk_bf16_f32 v39, v42, v43
	s_waitcnt lgkmcnt(4)
	v_mfma_f32_32x32x16_bf16 v[4:19], v[20:23], v[92:95], v[4:19]
	v_cvt_pk_bf16_f32 v20, v76, v77
	v_cvt_pk_bf16_f32 v21, v78, v79
	v_cvt_pk_bf16_f32 v22, v80, v81
	v_cvt_pk_bf16_f32 v23, v82, v83
	global_store_dwordx4 v[52:53], v[20:23], off offset:1024
	ds_read_b64_tr_b16 v[40:41], v153 offset:5312
	ds_read_b64_tr_b16 v[42:43], v153 offset:7872
	global_store_dwordx4 v[52:53], v[36:39], off offset:2048
	s_waitcnt lgkmcnt(4)
	v_mfma_f32_32x32x16_bf16 v[4:19], v[28:31], v[84:87], v[4:19]
	s_mul_i32 s6, s32, 0x200
	v_cvt_pk_bf16_f32 v36, v44, v45
	v_cvt_pk_bf16_f32 v37, v46, v47
	ds_read_b64_tr_b16 v[44:45], v153 offset:10432
	ds_read_b64_tr_b16 v[46:47], v153 offset:12992
	v_cvt_pk_bf16_f32 v38, v48, v49
	v_cvt_pk_bf16_f32 v39, v50, v51
	global_store_dwordx4 v[52:53], v[36:39], off offset:3072
	s_waitcnt lgkmcnt(4)
	v_mfma_f32_32x32x16_bf16 v[20:35], v[24:27], v[96:99], 0
	s_mov_b32 s7, 0
	s_nop 0
	v_cvt_pk_bf16_f32 v36, v4, v5
	v_cvt_pk_bf16_f32 v37, v6, v7
	ds_read_b64_tr_b16 v[4:5], v153 offset:15552
	ds_read_b64_tr_b16 v[6:7], v153 offset:18112
	v_cvt_pk_bf16_f32 v38, v8, v9
	v_add_co_u32_e64 v8, s[62:63], s97, v52
	s_waitcnt lgkmcnt(4)
	v_mfma_f32_32x32x16_bf16 v[20:35], v[40:43], v[88:91], v[20:35]
	v_addc_co_u32_e64 v9, s[62:63], 0, v53, s[62:63]
	v_cvt_pk_bf16_f32 v39, v10, v11
	v_cvt_pk_bf16_f32 v10, v12, v13
	v_cvt_pk_bf16_f32 v11, v14, v15
	v_cvt_pk_bf16_f32 v12, v16, v17
	v_cvt_pk_bf16_f32 v13, v18, v19
	s_waitcnt lgkmcnt(2)
	v_mfma_f32_32x32x16_bf16 v[20:35], v[44:47], v[92:95], v[20:35]
	v_lshl_add_u64 v[122:123], v[122:123], 0, s[6:7]
	s_mul_i32 s6, s32, 0x10000
	v_lshl_add_u64 v[120:121], v[120:121], 0, s[6:7]
	global_store_dwordx4 v[8:9], v[36:39], off
	global_store_dwordx4 v[8:9], v[10:13], off offset:1024
	s_waitcnt lgkmcnt(0)
	v_mfma_f32_32x32x16_bf16 v[20:35], v[4:7], v[84:87], v[20:35]
	s_nop 11
	v_cvt_pk_bf16_f32 v4, v20, v21
	v_cvt_pk_bf16_f32 v5, v22, v23
	v_cvt_pk_bf16_f32 v6, v24, v25
	v_cvt_pk_bf16_f32 v7, v26, v27
	global_store_dwordx4 v[8:9], v[4:7], off offset:2048
	s_nop 1
	v_cvt_pk_bf16_f32 v4, v28, v29
	v_cvt_pk_bf16_f32 v5, v30, v31
	v_cvt_pk_bf16_f32 v6, v32, v33
	v_cvt_pk_bf16_f32 v7, v34, v35
	global_store_dwordx4 v[8:9], v[4:7], off offset:3072
	s_barrier
; #define AIN(i) arg_in(i)
; __global__ void __launch_bounds__(NTHREADS, 2) fwd_megakernel(Args a) {
;     ...
;             for (int u = G - 1 - bx; u < nun; u += G) gla_a_unit(lds, PB, PB + PBE, FA, (unsigned char*)H, row0, (float*)((unsigned char*)H + WS_DECB), u >> 2, u & 3, AIN(10), AIN(11), tid);
	s_cbranch_scc1 .LBB0_564
